# tail units with rigorous deferred producer signal: all waves drain at unit 2, wave0 L2 write-back at unit 3, flag post at unit 4
# baseline (speedup 1.0000x reference)
.LBB0_331:
	s_cmp_eq_u32 s99, 0
	s_cbranch_scc1 .Lsd3_x
	s_cmp_lt_u32 s15, 3
	s_cbranch_scc1 .Lsd3_x
	s_cmp_gt_u32 s15, 5
	s_cbranch_scc1 .Lsd3_x
	s_cmp_lg_u32 s15, 3
	s_cbranch_scc1 .Lsd3_a
	s_waitcnt vmcnt(0)
	s_branch .Lsd3_x
.Lsd3_a:
	v_cmp_gt_u32_e32 vcc, 64, v175
	s_cbranch_vccz .Lsd3_x
	s_cmp_eq_u32 s15, 4
	s_cbranch_scc0 .Lsd3_b
	buffer_wbl2 sc1
	s_branch .Lsd3_x

.Ltl4_spin:
	global_load_dword v1, v0, s[94:95] sc1
	s_waitcnt vmcnt(0)
	v_readfirstlane_b32 s3, v1
	s_cmp_ge_u32 s3, 44
	s_cbranch_scc1 .Ltl4_rdy
	s_sleep 8
	s_add_u32 s99, s99, 1
	s_cmp_lt_u32 s99, 0x2000
	s_cbranch_scc1 .Ltl4_spin

.LBB0_1226:
	s_cmp_eq_u32 s99, 0
	s_cbranch_scc1 .Lsd11_x
	s_cmp_lt_u32 s46, 3
	s_cbranch_scc1 .Lsd11_x
	s_cmp_gt_u32 s46, 5
	s_cbranch_scc1 .Lsd11_x
	s_cmp_lg_u32 s46, 3
	s_cbranch_scc1 .Lsd11_a
	s_waitcnt vmcnt(0)
	s_branch .Lsd11_x
.Lsd11_a:
	v_cmp_gt_u32_e32 vcc, 64, v175
	s_cbranch_vccz .Lsd11_x
	s_cmp_eq_u32 s46, 4
	s_cbranch_scc0 .Lsd11_b
	buffer_wbl2 sc1
	s_branch .Lsd11_x

.Ltl12_spin:
	global_load_dword v1, v0, s[94:95] sc1
	s_waitcnt vmcnt(0)
	v_readfirstlane_b32 s3, v1
	s_cmp_ge_u32 s3, 88
	s_cbranch_scc1 .Ltl12_rdy
	s_sleep 8
	s_add_u32 s99, s99, 1
	s_cmp_lt_u32 s99, 0x2000
	s_cbranch_scc1 .Ltl12_spin
